# G1 rope epilogue regenerated: 16 table loads prefetched, next-half loads issued behind stores with counted vmcnt (no store-completion waits), batched packed math; bit-identical
# speedup vs baseline: 1.0091x; 1.0091x over previous
; __device__ __forceinline__ unsigned cvt_pk_bf16(float lo, float hi) { unsigned r; asm volatile("v_cvt_pk_bf16_f32 %0, %1, %2" : "=v"(r) : "v"(lo), "v"(hi)); return r; }
;     __device__ __forceinline__ void operator()(const f32x4 (&acc)[2][2][4][2], const Unit& u, int wr, int wc, int fr, int fq) const {
;         const int row0 = u.pm * BM + wr * 64 + fr;
;         if (u.pn < 8) {
;             const float sc = (u.pn < 4) ? QSCALE : 1.f;
;             const int col = u.pn * BM + 64 * wc + 8 * fq;
; #pragma unroll
;             for (int ai = 0; ai < 2; ++ai)
; #pragma unroll
;                 for (int m = 0; m < 4; ++m) { const int row = row0 + ai * HALF + m * 16; const int pos = row & 4095;
;                     const float rs = sc * rstd[row & 255];
;                     const f32x4 c0 = *(const f32x4*)(cosT + pos * 32 + 8 * fq), c1 = *(const f32x4*)(cosT + pos * 32 + 8 * fq + 4);
;                     const f32x4 s0 = *(const f32x4*)(sinT + pos * 32 + 8 * fq), s1 = *(const f32x4*)(sinT + pos * 32 + 8 * fq + 4);
;                     const f32x4 a0 = acc[ai][0][m][0], a1 = acc[ai][0][m][1], b0 = acc[ai][1][m][0], b1 = acc[ai][1][m][1];
;                     const f32x4 x0 = (a0 * c0 - b0 * s0) * rs, x1 = (a1 * c1 - b1 * s1) * rs, y0 = (b0 * c0 + a0 * s0) * rs, y1 = (b1 * c1 + a1 * s1) * rs;
;                     bf16_t* rowp = O + (size_t)row * ldc + col;
;                     u32x4 w; w.x = cvt_pk_bf16(x0[0], x0[1]); w.y = cvt_pk_bf16(x0[2], x0[3]); w.z = cvt_pk_bf16(x1[0], x1[1]); w.w = cvt_pk_bf16(x1[2], x1[3]);
;                     *(u32x4*)rowp = w;
;                     w.x = cvt_pk_bf16(y0[0], y0[1]); w.y = cvt_pk_bf16(y0[2], y0[3]); w.z = cvt_pk_bf16(y1[0], y1[1]); w.w = cvt_pk_bf16(y1[2], y1[3]);
;                     *(u32x4*)(rowp + 32) = w; }
.LBB0_142:
	v_lshlrev_b32_e32 v197, 7, v155
	v_and_b32_e32 v197, 0x7ff80, v197
	ds_read_b32 v250, v152
	v_mov_b32_e32 v162, v197
	v_lshl_add_u64 v[198:199], v[138:139], 0, v[162:163]
	global_load_dwordx4 v[174:177], v[198:199], off
	global_load_dwordx4 v[178:181], v[198:199], off offset:16
	v_lshl_add_u64 v[198:199], v[136:137], 0, v[162:163]
	global_load_dwordx4 v[182:185], v[198:199], off
	global_load_dwordx4 v[186:189], v[198:199], off offset:16
	v_or_b32_e32 v162, 0x800, v197
	v_lshl_add_u64 v[198:199], v[138:139], 0, v[162:163]
	global_load_dwordx4 v[206:209], v[198:199], off
	global_load_dwordx4 v[210:213], v[198:199], off offset:16
	v_lshl_add_u64 v[198:199], v[136:137], 0, v[162:163]
	global_load_dwordx4 v[214:217], v[198:199], off
	global_load_dwordx4 v[218:221], v[198:199], off offset:16
	v_or_b32_e32 v162, 0x1000, v197
	v_lshl_add_u64 v[198:199], v[138:139], 0, v[162:163]
	global_load_dwordx4 v[222:225], v[198:199], off
	global_load_dwordx4 v[226:229], v[198:199], off offset:16
	v_lshl_add_u64 v[198:199], v[136:137], 0, v[162:163]
	global_load_dwordx4 v[230:233], v[198:199], off
	global_load_dwordx4 v[234:237], v[198:199], off offset:16
	v_or_b32_e32 v162, 0x1800, v197
	v_lshl_add_u64 v[198:199], v[138:139], 0, v[162:163]
	global_load_dwordx4 v[238:241], v[198:199], off
	global_load_dwordx4 v[242:245], v[198:199], off offset:16
	v_lshl_add_u64 v[198:199], v[136:137], 0, v[162:163]
	global_load_dwordx4 v[144:147], v[198:199], off
	global_load_dwordx4 v[156:159], v[198:199], off offset:16
	v_mul_u32_u24_e32 v196, 0x3000, v155
	v_lshl_or_b32 v162, s76, 8, v153
	v_lshl_add_u32 v196, v162, 1, v196
	s_cmp_lt_i32 s76, 4
	s_cselect_b32 s21, 0x3e38aa3b, 1.0
	s_waitcnt lgkmcnt(0)
	v_mul_f32_e32 v250, s21, v250
	ds_read_b32 v251, v152 offset:64
	s_waitcnt vmcnt(12)
	v_pk_mul_f32 v[246:247], v[116:117], v[174:175]
	v_pk_mul_f32 v[174:175], v[124:125], v[174:175]
	v_pk_fma_f32 v[124:125], v[124:125], v[182:183], v[246:247] neg_lo:[0,0,1] neg_hi:[0,0,1]
	v_pk_fma_f32 v[116:117], v[116:117], v[182:183], v[174:175]
	v_pk_mul_f32 v[248:249], v[118:119], v[176:177]
	v_pk_mul_f32 v[176:177], v[126:127], v[176:177]
	v_pk_fma_f32 v[126:127], v[126:127], v[184:185], v[248:249] neg_lo:[0,0,1] neg_hi:[0,0,1]
	v_pk_fma_f32 v[118:119], v[118:119], v[184:185], v[176:177]
	v_pk_mul_f32 v[246:247], v[112:113], v[178:179]
	v_pk_mul_f32 v[178:179], v[120:121], v[178:179]
	v_pk_fma_f32 v[120:121], v[120:121], v[186:187], v[246:247] neg_lo:[0,0,1] neg_hi:[0,0,1]
	v_pk_fma_f32 v[112:113], v[112:113], v[186:187], v[178:179]
	v_pk_mul_f32 v[248:249], v[114:115], v[180:181]
	v_pk_mul_f32 v[180:181], v[122:123], v[180:181]
	v_pk_fma_f32 v[122:123], v[122:123], v[188:189], v[248:249] neg_lo:[0,0,1] neg_hi:[0,0,1]
	v_pk_fma_f32 v[114:115], v[114:115], v[188:189], v[180:181]
	v_pk_mul_f32 v[124:125], v[250:251], v[124:125] op_sel_hi:[0,1]
	v_pk_mul_f32 v[126:127], v[250:251], v[126:127] op_sel_hi:[0,1]
	v_pk_mul_f32 v[120:121], v[250:251], v[120:121] op_sel_hi:[0,1]
	v_pk_mul_f32 v[122:123], v[250:251], v[122:123] op_sel_hi:[0,1]
	v_pk_mul_f32 v[116:117], v[250:251], v[116:117] op_sel_hi:[0,1]
	v_pk_mul_f32 v[118:119], v[250:251], v[118:119] op_sel_hi:[0,1]
	v_pk_mul_f32 v[112:113], v[250:251], v[112:113] op_sel_hi:[0,1]
	v_pk_mul_f32 v[114:115], v[250:251], v[114:115] op_sel_hi:[0,1]
	v_cvt_pk_bf16_f32 v182, v124, v125
	v_cvt_pk_bf16_f32 v183, v126, v127
	v_cvt_pk_bf16_f32 v184, v120, v121
	v_cvt_pk_bf16_f32 v185, v122, v123
	v_cvt_pk_bf16_f32 v186, v116, v117
	v_cvt_pk_bf16_f32 v187, v118, v119
	v_cvt_pk_bf16_f32 v188, v112, v113
	v_cvt_pk_bf16_f32 v189, v114, v115
	v_mov_b32_e32 v246, v196
	global_store_dwordx4 v246, v[182:185], s[66:67]
	global_store_dwordx4 v246, v[186:189], s[66:67] offset:64
	v_or_b32_e32 v162, 0x4000, v197
	v_lshl_add_u64 v[198:199], v[138:139], 0, v[162:163]
	global_load_dwordx4 v[124:127], v[198:199], off
	global_load_dwordx4 v[120:123], v[198:199], off offset:16
	v_lshl_add_u64 v[198:199], v[136:137], 0, v[162:163]
	global_load_dwordx4 v[116:119], v[198:199], off
	global_load_dwordx4 v[112:115], v[198:199], off offset:16
	s_waitcnt lgkmcnt(0)
	v_mul_f32_e32 v251, s21, v251
	ds_read_b32 v250, v152 offset:128
	s_waitcnt vmcnt(14)
	v_pk_mul_f32 v[246:247], v[100:101], v[206:207]
	v_pk_mul_f32 v[206:207], v[108:109], v[206:207]
	v_pk_fma_f32 v[108:109], v[108:109], v[214:215], v[246:247] neg_lo:[0,0,1] neg_hi:[0,0,1]
	v_pk_fma_f32 v[100:101], v[100:101], v[214:215], v[206:207]
	v_pk_mul_f32 v[248:249], v[102:103], v[208:209]
	v_pk_mul_f32 v[208:209], v[110:111], v[208:209]
	v_pk_fma_f32 v[110:111], v[110:111], v[216:217], v[248:249] neg_lo:[0,0,1] neg_hi:[0,0,1]
	v_pk_fma_f32 v[102:103], v[102:103], v[216:217], v[208:209]
	v_pk_mul_f32 v[246:247], v[96:97], v[210:211]
	v_pk_mul_f32 v[210:211], v[104:105], v[210:211]
	v_pk_fma_f32 v[104:105], v[104:105], v[218:219], v[246:247] neg_lo:[0,0,1] neg_hi:[0,0,1]
	v_pk_fma_f32 v[96:97], v[96:97], v[218:219], v[210:211]
	v_pk_mul_f32 v[248:249], v[98:99], v[212:213]
	v_pk_mul_f32 v[212:213], v[106:107], v[212:213]
	v_pk_fma_f32 v[106:107], v[106:107], v[220:221], v[248:249] neg_lo:[0,0,1] neg_hi:[0,0,1]
	v_pk_fma_f32 v[98:99], v[98:99], v[220:221], v[212:213]
	v_pk_mul_f32 v[108:109], v[250:251], v[108:109] op_sel:[1,0] op_sel_hi:[1,1]
	v_pk_mul_f32 v[110:111], v[250:251], v[110:111] op_sel:[1,0] op_sel_hi:[1,1]
	v_pk_mul_f32 v[104:105], v[250:251], v[104:105] op_sel:[1,0] op_sel_hi:[1,1]
	v_pk_mul_f32 v[106:107], v[250:251], v[106:107] op_sel:[1,0] op_sel_hi:[1,1]
	v_pk_mul_f32 v[100:101], v[250:251], v[100:101] op_sel:[1,0] op_sel_hi:[1,1]
	v_pk_mul_f32 v[102:103], v[250:251], v[102:103] op_sel:[1,0] op_sel_hi:[1,1]
	v_pk_mul_f32 v[96:97], v[250:251], v[96:97] op_sel:[1,0] op_sel_hi:[1,1]
	v_pk_mul_f32 v[98:99], v[250:251], v[98:99] op_sel:[1,0] op_sel_hi:[1,1]
	v_cvt_pk_bf16_f32 v214, v108, v109
	v_cvt_pk_bf16_f32 v215, v110, v111
	v_cvt_pk_bf16_f32 v216, v104, v105
	v_cvt_pk_bf16_f32 v217, v106, v107
	v_cvt_pk_bf16_f32 v218, v100, v101
	v_cvt_pk_bf16_f32 v219, v102, v103
	v_cvt_pk_bf16_f32 v220, v96, v97
	v_cvt_pk_bf16_f32 v221, v98, v99
	v_add_u32_e32 v246, 0x30000, v196
	global_store_dwordx4 v246, v[214:217], s[66:67]
	global_store_dwordx4 v246, v[218:221], s[66:67] offset:64
	v_or_b32_e32 v162, 0x4800, v197
	v_lshl_add_u64 v[198:199], v[138:139], 0, v[162:163]
	global_load_dwordx4 v[108:111], v[198:199], off
	global_load_dwordx4 v[104:107], v[198:199], off offset:16
	v_lshl_add_u64 v[198:199], v[136:137], 0, v[162:163]
	global_load_dwordx4 v[100:103], v[198:199], off
	global_load_dwordx4 v[96:99], v[198:199], off offset:16
	s_waitcnt lgkmcnt(0)
; __device__ __forceinline__ unsigned cvt_pk_bf16(float lo, float hi) { unsigned r; asm volatile("v_cvt_pk_bf16_f32 %0, %1, %2" : "=v"(r) : "v"(lo), "v"(hi)); return r; }
;     __device__ __forceinline__ void operator()(const f32x4 (&acc)[2][2][4][2], const Unit& u, int wr, int wc, int fr, int fq) const {
;         const int row0 = u.pm * BM + wr * 64 + fr;
;         if (u.pn < 8) {
;             const float sc = (u.pn < 4) ? QSCALE : 1.f;
;             const int col = u.pn * BM + 64 * wc + 8 * fq;
; #pragma unroll
;             for (int ai = 0; ai < 2; ++ai)
; #pragma unroll
;                 for (int m = 0; m < 4; ++m) { const int row = row0 + ai * HALF + m * 16; const int pos = row & 4095;
;                     const float rs = sc * rstd[row & 255];
;                     const f32x4 c0 = *(const f32x4*)(cosT + pos * 32 + 8 * fq), c1 = *(const f32x4*)(cosT + pos * 32 + 8 * fq + 4);
;                     const f32x4 s0 = *(const f32x4*)(sinT + pos * 32 + 8 * fq), s1 = *(const f32x4*)(sinT + pos * 32 + 8 * fq + 4);
;                     const f32x4 a0 = acc[ai][0][m][0], a1 = acc[ai][0][m][1], b0 = acc[ai][1][m][0], b1 = acc[ai][1][m][1];
;                     const f32x4 x0 = (a0 * c0 - b0 * s0) * rs, x1 = (a1 * c1 - b1 * s1) * rs, y0 = (b0 * c0 + a0 * s0) * rs, y1 = (b1 * c1 + a1 * s1) * rs;
;                     bf16_t* rowp = O + (size_t)row * ldc + col;
;                     u32x4 w; w.x = cvt_pk_bf16(x0[0], x0[1]); w.y = cvt_pk_bf16(x0[2], x0[3]); w.z = cvt_pk_bf16(x1[0], x1[1]); w.w = cvt_pk_bf16(x1[2], x1[3]);
;                     *(u32x4*)rowp = w;
;                     w.x = cvt_pk_bf16(y0[0], y0[1]); w.y = cvt_pk_bf16(y0[2], y0[3]); w.z = cvt_pk_bf16(y1[0], y1[1]); w.w = cvt_pk_bf16(y1[2], y1[3]);
;                     *(u32x4*)(rowp + 32) = w; }
	v_mul_f32_e32 v250, s21, v250
	ds_read_b32 v251, v152 offset:192
	s_waitcnt vmcnt(16)
	v_pk_mul_f32 v[246:247], v[84:85], v[222:223]
	v_pk_mul_f32 v[222:223], v[92:93], v[222:223]
	v_pk_fma_f32 v[92:93], v[92:93], v[230:231], v[246:247] neg_lo:[0,0,1] neg_hi:[0,0,1]
	v_pk_fma_f32 v[84:85], v[84:85], v[230:231], v[222:223]
	v_pk_mul_f32 v[248:249], v[86:87], v[224:225]
	v_pk_mul_f32 v[224:225], v[94:95], v[224:225]
	v_pk_fma_f32 v[94:95], v[94:95], v[232:233], v[248:249] neg_lo:[0,0,1] neg_hi:[0,0,1]
	v_pk_fma_f32 v[86:87], v[86:87], v[232:233], v[224:225]
	v_pk_mul_f32 v[246:247], v[80:81], v[226:227]
	v_pk_mul_f32 v[226:227], v[88:89], v[226:227]
	v_pk_fma_f32 v[88:89], v[88:89], v[234:235], v[246:247] neg_lo:[0,0,1] neg_hi:[0,0,1]
	v_pk_fma_f32 v[80:81], v[80:81], v[234:235], v[226:227]
	v_pk_mul_f32 v[248:249], v[82:83], v[228:229]
	v_pk_mul_f32 v[228:229], v[90:91], v[228:229]
	v_pk_fma_f32 v[90:91], v[90:91], v[236:237], v[248:249] neg_lo:[0,0,1] neg_hi:[0,0,1]
	v_pk_fma_f32 v[82:83], v[82:83], v[236:237], v[228:229]
	v_pk_mul_f32 v[92:93], v[250:251], v[92:93] op_sel_hi:[0,1]
	v_pk_mul_f32 v[94:95], v[250:251], v[94:95] op_sel_hi:[0,1]
	v_pk_mul_f32 v[88:89], v[250:251], v[88:89] op_sel_hi:[0,1]
	v_pk_mul_f32 v[90:91], v[250:251], v[90:91] op_sel_hi:[0,1]
	v_pk_mul_f32 v[84:85], v[250:251], v[84:85] op_sel_hi:[0,1]
	v_pk_mul_f32 v[86:87], v[250:251], v[86:87] op_sel_hi:[0,1]
	v_pk_mul_f32 v[80:81], v[250:251], v[80:81] op_sel_hi:[0,1]
	v_pk_mul_f32 v[82:83], v[250:251], v[82:83] op_sel_hi:[0,1]
	v_cvt_pk_bf16_f32 v230, v92, v93
	v_cvt_pk_bf16_f32 v231, v94, v95
	v_cvt_pk_bf16_f32 v232, v88, v89
	v_cvt_pk_bf16_f32 v233, v90, v91
	v_cvt_pk_bf16_f32 v234, v84, v85
	v_cvt_pk_bf16_f32 v235, v86, v87
	v_cvt_pk_bf16_f32 v236, v80, v81
	v_cvt_pk_bf16_f32 v237, v82, v83
	v_add_u32_e32 v246, 0x60000, v196
	global_store_dwordx4 v246, v[230:233], s[66:67]
	global_store_dwordx4 v246, v[234:237], s[66:67] offset:64
	v_or_b32_e32 v162, 0x5000, v197
	v_lshl_add_u64 v[198:199], v[138:139], 0, v[162:163]
	global_load_dwordx4 v[92:95], v[198:199], off
	global_load_dwordx4 v[88:91], v[198:199], off offset:16
	v_lshl_add_u64 v[198:199], v[136:137], 0, v[162:163]
	global_load_dwordx4 v[84:87], v[198:199], off
	global_load_dwordx4 v[80:83], v[198:199], off offset:16
	s_waitcnt lgkmcnt(0)
	v_mul_f32_e32 v251, s21, v251
	ds_read_b32 v250, v152 offset:512
	s_waitcnt vmcnt(18)
	v_pk_mul_f32 v[246:247], v[68:69], v[238:239]
	v_pk_mul_f32 v[238:239], v[76:77], v[238:239]
	v_pk_fma_f32 v[76:77], v[76:77], v[144:145], v[246:247] neg_lo:[0,0,1] neg_hi:[0,0,1]
	v_pk_fma_f32 v[68:69], v[68:69], v[144:145], v[238:239]
	v_pk_mul_f32 v[248:249], v[70:71], v[240:241]
	v_pk_mul_f32 v[240:241], v[78:79], v[240:241]
	v_pk_fma_f32 v[78:79], v[78:79], v[146:147], v[248:249] neg_lo:[0,0,1] neg_hi:[0,0,1]
	v_pk_fma_f32 v[70:71], v[70:71], v[146:147], v[240:241]
	v_pk_mul_f32 v[246:247], v[64:65], v[242:243]
	v_pk_mul_f32 v[242:243], v[72:73], v[242:243]
	v_pk_fma_f32 v[72:73], v[72:73], v[156:157], v[246:247] neg_lo:[0,0,1] neg_hi:[0,0,1]
	v_pk_fma_f32 v[64:65], v[64:65], v[156:157], v[242:243]
	v_pk_mul_f32 v[248:249], v[66:67], v[244:245]
	v_pk_mul_f32 v[244:245], v[74:75], v[244:245]
	v_pk_fma_f32 v[74:75], v[74:75], v[158:159], v[248:249] neg_lo:[0,0,1] neg_hi:[0,0,1]
	v_pk_fma_f32 v[66:67], v[66:67], v[158:159], v[244:245]
	v_pk_mul_f32 v[76:77], v[250:251], v[76:77] op_sel:[1,0] op_sel_hi:[1,1]
	v_pk_mul_f32 v[78:79], v[250:251], v[78:79] op_sel:[1,0] op_sel_hi:[1,1]
	v_pk_mul_f32 v[72:73], v[250:251], v[72:73] op_sel:[1,0] op_sel_hi:[1,1]
	v_pk_mul_f32 v[74:75], v[250:251], v[74:75] op_sel:[1,0] op_sel_hi:[1,1]
	v_pk_mul_f32 v[68:69], v[250:251], v[68:69] op_sel:[1,0] op_sel_hi:[1,1]
	v_pk_mul_f32 v[70:71], v[250:251], v[70:71] op_sel:[1,0] op_sel_hi:[1,1]
	v_pk_mul_f32 v[64:65], v[250:251], v[64:65] op_sel:[1,0] op_sel_hi:[1,1]
	v_pk_mul_f32 v[66:67], v[250:251], v[66:67] op_sel:[1,0] op_sel_hi:[1,1]
	v_cvt_pk_bf16_f32 v144, v76, v77
	v_cvt_pk_bf16_f32 v145, v78, v79
	v_cvt_pk_bf16_f32 v146, v72, v73
	v_cvt_pk_bf16_f32 v147, v74, v75
	v_cvt_pk_bf16_f32 v156, v68, v69
	v_cvt_pk_bf16_f32 v157, v70, v71
	v_cvt_pk_bf16_f32 v158, v64, v65
	v_cvt_pk_bf16_f32 v159, v66, v67
	v_add_u32_e32 v246, 0x90000, v196
	global_store_dwordx4 v246, v[144:147], s[66:67]
	global_store_dwordx4 v246, v[156:159], s[66:67] offset:64
	v_or_b32_e32 v162, 0x5800, v197
	v_lshl_add_u64 v[198:199], v[138:139], 0, v[162:163]
	global_load_dwordx4 v[76:79], v[198:199], off
	global_load_dwordx4 v[72:75], v[198:199], off offset:16
	v_lshl_add_u64 v[198:199], v[136:137], 0, v[162:163]
	global_load_dwordx4 v[68:71], v[198:199], off
	global_load_dwordx4 v[64:67], v[198:199], off offset:16
	s_waitcnt lgkmcnt(0)
	v_mul_f32_e32 v250, s21, v250
	ds_read_b32 v251, v152 offset:576
	s_waitcnt vmcnt(18)
; __device__ __forceinline__ unsigned cvt_pk_bf16(float lo, float hi) { unsigned r; asm volatile("v_cvt_pk_bf16_f32 %0, %1, %2" : "=v"(r) : "v"(lo), "v"(hi)); return r; }
;     __device__ __forceinline__ void operator()(const f32x4 (&acc)[2][2][4][2], const Unit& u, int wr, int wc, int fr, int fq) const {
;         const int row0 = u.pm * BM + wr * 64 + fr;
;         if (u.pn < 8) {
;             const float sc = (u.pn < 4) ? QSCALE : 1.f;
;             const int col = u.pn * BM + 64 * wc + 8 * fq;
; #pragma unroll
;             for (int ai = 0; ai < 2; ++ai)
; #pragma unroll
;                 for (int m = 0; m < 4; ++m) { const int row = row0 + ai * HALF + m * 16; const int pos = row & 4095;
;                     const float rs = sc * rstd[row & 255];
;                     const f32x4 c0 = *(const f32x4*)(cosT + pos * 32 + 8 * fq), c1 = *(const f32x4*)(cosT + pos * 32 + 8 * fq + 4);
;                     const f32x4 s0 = *(const f32x4*)(sinT + pos * 32 + 8 * fq), s1 = *(const f32x4*)(sinT + pos * 32 + 8 * fq + 4);
;                     const f32x4 a0 = acc[ai][0][m][0], a1 = acc[ai][0][m][1], b0 = acc[ai][1][m][0], b1 = acc[ai][1][m][1];
;                     const f32x4 x0 = (a0 * c0 - b0 * s0) * rs, x1 = (a1 * c1 - b1 * s1) * rs, y0 = (b0 * c0 + a0 * s0) * rs, y1 = (b1 * c1 + a1 * s1) * rs;
;                     bf16_t* rowp = O + (size_t)row * ldc + col;
;                     u32x4 w; w.x = cvt_pk_bf16(x0[0], x0[1]); w.y = cvt_pk_bf16(x0[2], x0[3]); w.z = cvt_pk_bf16(x1[0], x1[1]); w.w = cvt_pk_bf16(x1[2], x1[3]);
;                     *(u32x4*)rowp = w;
;                     w.x = cvt_pk_bf16(y0[0], y0[1]); w.y = cvt_pk_bf16(y0[2], y0[3]); w.z = cvt_pk_bf16(y1[0], y1[1]); w.w = cvt_pk_bf16(y1[2], y1[3]);
;                     *(u32x4*)(rowp + 32) = w; }
	v_pk_mul_f32 v[246:247], v[52:53], v[124:125]
	v_pk_mul_f32 v[124:125], v[60:61], v[124:125]
	v_pk_fma_f32 v[60:61], v[60:61], v[116:117], v[246:247] neg_lo:[0,0,1] neg_hi:[0,0,1]
	v_pk_fma_f32 v[52:53], v[52:53], v[116:117], v[124:125]
	v_pk_mul_f32 v[248:249], v[54:55], v[126:127]
	v_pk_mul_f32 v[126:127], v[62:63], v[126:127]
	v_pk_fma_f32 v[62:63], v[62:63], v[118:119], v[248:249] neg_lo:[0,0,1] neg_hi:[0,0,1]
	v_pk_fma_f32 v[54:55], v[54:55], v[118:119], v[126:127]
	v_pk_mul_f32 v[246:247], v[48:49], v[120:121]
	v_pk_mul_f32 v[120:121], v[56:57], v[120:121]
	v_pk_fma_f32 v[56:57], v[56:57], v[112:113], v[246:247] neg_lo:[0,0,1] neg_hi:[0,0,1]
	v_pk_fma_f32 v[48:49], v[48:49], v[112:113], v[120:121]
	v_pk_mul_f32 v[248:249], v[50:51], v[122:123]
	v_pk_mul_f32 v[122:123], v[58:59], v[122:123]
	v_pk_fma_f32 v[58:59], v[58:59], v[114:115], v[248:249] neg_lo:[0,0,1] neg_hi:[0,0,1]
	v_pk_fma_f32 v[50:51], v[50:51], v[114:115], v[122:123]
	v_pk_mul_f32 v[60:61], v[250:251], v[60:61] op_sel_hi:[0,1]
	v_pk_mul_f32 v[62:63], v[250:251], v[62:63] op_sel_hi:[0,1]
	v_pk_mul_f32 v[56:57], v[250:251], v[56:57] op_sel_hi:[0,1]
	v_pk_mul_f32 v[58:59], v[250:251], v[58:59] op_sel_hi:[0,1]
	v_pk_mul_f32 v[52:53], v[250:251], v[52:53] op_sel_hi:[0,1]
	v_pk_mul_f32 v[54:55], v[250:251], v[54:55] op_sel_hi:[0,1]
	v_pk_mul_f32 v[48:49], v[250:251], v[48:49] op_sel_hi:[0,1]
	v_pk_mul_f32 v[50:51], v[250:251], v[50:51] op_sel_hi:[0,1]
	v_cvt_pk_bf16_f32 v116, v60, v61
	v_cvt_pk_bf16_f32 v117, v62, v63
	v_cvt_pk_bf16_f32 v118, v56, v57
	v_cvt_pk_bf16_f32 v119, v58, v59
	v_cvt_pk_bf16_f32 v112, v52, v53
	v_cvt_pk_bf16_f32 v113, v54, v55
	v_cvt_pk_bf16_f32 v114, v48, v49
	v_cvt_pk_bf16_f32 v115, v50, v51
	v_add_u32_e32 v246, 0x180000, v196
	global_store_dwordx4 v246, v[116:119], s[66:67]
	global_store_dwordx4 v246, v[112:115], s[66:67] offset:64
	s_waitcnt lgkmcnt(0)
	v_mul_f32_e32 v251, s21, v251
	ds_read_b32 v250, v152 offset:640
	s_waitcnt vmcnt(14)
	v_pk_mul_f32 v[246:247], v[36:37], v[108:109]
	v_pk_mul_f32 v[108:109], v[44:45], v[108:109]
	v_pk_fma_f32 v[44:45], v[44:45], v[100:101], v[246:247] neg_lo:[0,0,1] neg_hi:[0,0,1]
	v_pk_fma_f32 v[36:37], v[36:37], v[100:101], v[108:109]
	v_pk_mul_f32 v[248:249], v[38:39], v[110:111]
	v_pk_mul_f32 v[110:111], v[46:47], v[110:111]
	v_pk_fma_f32 v[46:47], v[46:47], v[102:103], v[248:249] neg_lo:[0,0,1] neg_hi:[0,0,1]
	v_pk_fma_f32 v[38:39], v[38:39], v[102:103], v[110:111]
	v_pk_mul_f32 v[246:247], v[32:33], v[104:105]
	v_pk_mul_f32 v[104:105], v[40:41], v[104:105]
	v_pk_fma_f32 v[40:41], v[40:41], v[96:97], v[246:247] neg_lo:[0,0,1] neg_hi:[0,0,1]
	v_pk_fma_f32 v[32:33], v[32:33], v[96:97], v[104:105]
	v_pk_mul_f32 v[248:249], v[34:35], v[106:107]
	v_pk_mul_f32 v[106:107], v[42:43], v[106:107]
	v_pk_fma_f32 v[42:43], v[42:43], v[98:99], v[248:249] neg_lo:[0,0,1] neg_hi:[0,0,1]
	v_pk_fma_f32 v[34:35], v[34:35], v[98:99], v[106:107]
	v_pk_mul_f32 v[44:45], v[250:251], v[44:45] op_sel:[1,0] op_sel_hi:[1,1]
	v_pk_mul_f32 v[46:47], v[250:251], v[46:47] op_sel:[1,0] op_sel_hi:[1,1]
	v_pk_mul_f32 v[40:41], v[250:251], v[40:41] op_sel:[1,0] op_sel_hi:[1,1]
	v_pk_mul_f32 v[42:43], v[250:251], v[42:43] op_sel:[1,0] op_sel_hi:[1,1]
	v_pk_mul_f32 v[36:37], v[250:251], v[36:37] op_sel:[1,0] op_sel_hi:[1,1]
	v_pk_mul_f32 v[38:39], v[250:251], v[38:39] op_sel:[1,0] op_sel_hi:[1,1]
	v_pk_mul_f32 v[32:33], v[250:251], v[32:33] op_sel:[1,0] op_sel_hi:[1,1]
	v_pk_mul_f32 v[34:35], v[250:251], v[34:35] op_sel:[1,0] op_sel_hi:[1,1]
	v_cvt_pk_bf16_f32 v100, v44, v45
	v_cvt_pk_bf16_f32 v101, v46, v47
	v_cvt_pk_bf16_f32 v102, v40, v41
	v_cvt_pk_bf16_f32 v103, v42, v43
	v_cvt_pk_bf16_f32 v96, v36, v37
	v_cvt_pk_bf16_f32 v97, v38, v39
	v_cvt_pk_bf16_f32 v98, v32, v33
	v_cvt_pk_bf16_f32 v99, v34, v35
	v_add_u32_e32 v246, 0x1b0000, v196
	global_store_dwordx4 v246, v[100:103], s[66:67]
	global_store_dwordx4 v246, v[96:99], s[66:67] offset:64
	s_waitcnt lgkmcnt(0)
; __device__ __forceinline__ unsigned cvt_pk_bf16(float lo, float hi) { unsigned r; asm volatile("v_cvt_pk_bf16_f32 %0, %1, %2" : "=v"(r) : "v"(lo), "v"(hi)); return r; }
;     __device__ __forceinline__ void operator()(const f32x4 (&acc)[2][2][4][2], const Unit& u, int wr, int wc, int fr, int fq) const {
;         const int row0 = u.pm * BM + wr * 64 + fr;
;         if (u.pn < 8) {
;             const float sc = (u.pn < 4) ? QSCALE : 1.f;
;             const int col = u.pn * BM + 64 * wc + 8 * fq;
; #pragma unroll
;             for (int ai = 0; ai < 2; ++ai)
; #pragma unroll
;                 for (int m = 0; m < 4; ++m) { const int row = row0 + ai * HALF + m * 16; const int pos = row & 4095;
;                     const float rs = sc * rstd[row & 255];
;                     const f32x4 c0 = *(const f32x4*)(cosT + pos * 32 + 8 * fq), c1 = *(const f32x4*)(cosT + pos * 32 + 8 * fq + 4);
;                     const f32x4 s0 = *(const f32x4*)(sinT + pos * 32 + 8 * fq), s1 = *(const f32x4*)(sinT + pos * 32 + 8 * fq + 4);
;                     const f32x4 a0 = acc[ai][0][m][0], a1 = acc[ai][0][m][1], b0 = acc[ai][1][m][0], b1 = acc[ai][1][m][1];
;                     const f32x4 x0 = (a0 * c0 - b0 * s0) * rs, x1 = (a1 * c1 - b1 * s1) * rs, y0 = (b0 * c0 + a0 * s0) * rs, y1 = (b1 * c1 + a1 * s1) * rs;
;                     bf16_t* rowp = O + (size_t)row * ldc + col;
;                     u32x4 w; w.x = cvt_pk_bf16(x0[0], x0[1]); w.y = cvt_pk_bf16(x0[2], x0[3]); w.z = cvt_pk_bf16(x1[0], x1[1]); w.w = cvt_pk_bf16(x1[2], x1[3]);
;                     *(u32x4*)rowp = w;
;                     w.x = cvt_pk_bf16(y0[0], y0[1]); w.y = cvt_pk_bf16(y0[2], y0[3]); w.z = cvt_pk_bf16(y1[0], y1[1]); w.w = cvt_pk_bf16(y1[2], y1[3]);
;                     *(u32x4*)(rowp + 32) = w; }
	v_mul_f32_e32 v250, s21, v250
	ds_read_b32 v251, v152 offset:704
	s_waitcnt vmcnt(10)
	v_pk_mul_f32 v[246:247], v[20:21], v[92:93]
	v_pk_mul_f32 v[92:93], v[28:29], v[92:93]
	v_pk_fma_f32 v[28:29], v[28:29], v[84:85], v[246:247] neg_lo:[0,0,1] neg_hi:[0,0,1]
	v_pk_fma_f32 v[20:21], v[20:21], v[84:85], v[92:93]
	v_pk_mul_f32 v[248:249], v[22:23], v[94:95]
	v_pk_mul_f32 v[94:95], v[30:31], v[94:95]
	v_pk_fma_f32 v[30:31], v[30:31], v[86:87], v[248:249] neg_lo:[0,0,1] neg_hi:[0,0,1]
	v_pk_fma_f32 v[22:23], v[22:23], v[86:87], v[94:95]
	v_pk_mul_f32 v[246:247], v[16:17], v[88:89]
	v_pk_mul_f32 v[88:89], v[24:25], v[88:89]
	v_pk_fma_f32 v[24:25], v[24:25], v[80:81], v[246:247] neg_lo:[0,0,1] neg_hi:[0,0,1]
	v_pk_fma_f32 v[16:17], v[16:17], v[80:81], v[88:89]
	v_pk_mul_f32 v[248:249], v[18:19], v[90:91]
	v_pk_mul_f32 v[90:91], v[26:27], v[90:91]
	v_pk_fma_f32 v[26:27], v[26:27], v[82:83], v[248:249] neg_lo:[0,0,1] neg_hi:[0,0,1]
	v_pk_fma_f32 v[18:19], v[18:19], v[82:83], v[90:91]
	v_pk_mul_f32 v[28:29], v[250:251], v[28:29] op_sel_hi:[0,1]
	v_pk_mul_f32 v[30:31], v[250:251], v[30:31] op_sel_hi:[0,1]
	v_pk_mul_f32 v[24:25], v[250:251], v[24:25] op_sel_hi:[0,1]
	v_pk_mul_f32 v[26:27], v[250:251], v[26:27] op_sel_hi:[0,1]
	v_pk_mul_f32 v[20:21], v[250:251], v[20:21] op_sel_hi:[0,1]
	v_pk_mul_f32 v[22:23], v[250:251], v[22:23] op_sel_hi:[0,1]
	v_pk_mul_f32 v[16:17], v[250:251], v[16:17] op_sel_hi:[0,1]
	v_pk_mul_f32 v[18:19], v[250:251], v[18:19] op_sel_hi:[0,1]
	v_cvt_pk_bf16_f32 v84, v28, v29
	v_cvt_pk_bf16_f32 v85, v30, v31
	v_cvt_pk_bf16_f32 v86, v24, v25
	v_cvt_pk_bf16_f32 v87, v26, v27
	v_cvt_pk_bf16_f32 v80, v20, v21
	v_cvt_pk_bf16_f32 v81, v22, v23
	v_cvt_pk_bf16_f32 v82, v16, v17
	v_cvt_pk_bf16_f32 v83, v18, v19
	v_add_u32_e32 v246, 0x1e0000, v196
	global_store_dwordx4 v246, v[84:87], s[66:67]
	global_store_dwordx4 v246, v[80:83], s[66:67] offset:64
	s_waitcnt lgkmcnt(0)
	v_mul_f32_e32 v251, s21, v251
	s_waitcnt vmcnt(6)
	v_pk_mul_f32 v[246:247], v[4:5], v[76:77]
	v_pk_mul_f32 v[76:77], v[12:13], v[76:77]
	v_pk_fma_f32 v[12:13], v[12:13], v[68:69], v[246:247] neg_lo:[0,0,1] neg_hi:[0,0,1]
	v_pk_fma_f32 v[4:5], v[4:5], v[68:69], v[76:77]
	v_pk_mul_f32 v[248:249], v[6:7], v[78:79]
	v_pk_mul_f32 v[78:79], v[14:15], v[78:79]
	v_pk_fma_f32 v[14:15], v[14:15], v[70:71], v[248:249] neg_lo:[0,0,1] neg_hi:[0,0,1]
	v_pk_fma_f32 v[6:7], v[6:7], v[70:71], v[78:79]
	v_pk_mul_f32 v[246:247], v[0:1], v[72:73]
	v_pk_mul_f32 v[72:73], v[8:9], v[72:73]
	v_pk_fma_f32 v[8:9], v[8:9], v[64:65], v[246:247] neg_lo:[0,0,1] neg_hi:[0,0,1]
	v_pk_fma_f32 v[0:1], v[0:1], v[64:65], v[72:73]
	v_pk_mul_f32 v[248:249], v[2:3], v[74:75]
	v_pk_mul_f32 v[74:75], v[10:11], v[74:75]
	v_pk_fma_f32 v[10:11], v[10:11], v[66:67], v[248:249] neg_lo:[0,0,1] neg_hi:[0,0,1]
	v_pk_fma_f32 v[2:3], v[2:3], v[66:67], v[74:75]
	v_pk_mul_f32 v[12:13], v[250:251], v[12:13] op_sel:[1,0] op_sel_hi:[1,1]
	v_pk_mul_f32 v[14:15], v[250:251], v[14:15] op_sel:[1,0] op_sel_hi:[1,1]
	v_pk_mul_f32 v[8:9], v[250:251], v[8:9] op_sel:[1,0] op_sel_hi:[1,1]
	v_pk_mul_f32 v[10:11], v[250:251], v[10:11] op_sel:[1,0] op_sel_hi:[1,1]
	v_pk_mul_f32 v[4:5], v[250:251], v[4:5] op_sel:[1,0] op_sel_hi:[1,1]
	v_pk_mul_f32 v[6:7], v[250:251], v[6:7] op_sel:[1,0] op_sel_hi:[1,1]
	v_pk_mul_f32 v[0:1], v[250:251], v[0:1] op_sel:[1,0] op_sel_hi:[1,1]
	v_pk_mul_f32 v[2:3], v[250:251], v[2:3] op_sel:[1,0] op_sel_hi:[1,1]
	v_cvt_pk_bf16_f32 v68, v12, v13
	v_cvt_pk_bf16_f32 v69, v14, v15
	v_cvt_pk_bf16_f32 v70, v8, v9
	v_cvt_pk_bf16_f32 v71, v10, v11
	v_cvt_pk_bf16_f32 v64, v4, v5
	v_cvt_pk_bf16_f32 v65, v6, v7
	v_cvt_pk_bf16_f32 v66, v0, v1
	v_cvt_pk_bf16_f32 v67, v2, v3
	v_add_u32_e32 v246, 0x210000, v196
	global_store_dwordx4 v246, v[68:71], s[66:67]
	global_store_dwordx4 v246, v[64:67], s[66:67] offset:64
	s_andn2_b64 vcc, exec, s[38:39]
	s_mov_b64 s[20:21], -1
	s_cbranch_vccnz .LBB0_134
	s_branch .LBB0_150
